# P0 rmsnorm pass: next trip's two rows prefetched into shadow registers (software pipelining), in-body load waits removed
# speedup vs baseline: 1.0237x; 1.0015x over previous
; __device__ __forceinline__ void rms_pass(const float* X, const float* g, bf16_t* O, float* F, int rows, int gw, int NGW) {
;     ...
;     for (int m = gw; m < rows; m += 2 * NGW) {
;         const bool two = (m + NGW) < rows; const int m1 = two ? m + NGW : m;
;         const f32x4* x0 = (const f32x4*)(X + (size_t)m * 1024) + lane; const f32x4* x1 = (const f32x4*)(X + (size_t)m1 * 1024) + lane;
;         f32x4 v0[4], v1[4]; float s0 = 0.f, s1 = 0.f;
; #pragma unroll
;         for (int j = 0; j < 4; ++j) { v0[j] = x0[64 * j]; v1[j] = x1[64 * j]; }
.LBB0_1320:
	v_writelane_b32 v253, s30, 8
	s_nop 1
	v_writelane_b32 v253, s31, 9
	s_or_b64 exec, exec, s[4:5]
	s_add_u32 s94, s86, 0x14100000
	s_load_dwordx2 s[4:5], s[82:83], 0x0
	s_addc_u32 s95, s87, 0
	s_cmp_lt_i32 s78, 0x10000
	s_cselect_b64 s[6:7], -1, 0
	v_mov_b32_e32 v2, v198
	v_writelane_b32 v253, s6, 6
	s_cmp_gt_i32 s78, 0xffff
	v_mbcnt_lo_u32_b32 v199, -1, 0
	v_writelane_b32 v253, s7, 7
	s_cbranch_scc1 .LBB0_1331
	s_load_dwordx2 s[6:7], s[82:83], 0x10
	v_and_b32_e32 v4, 63, v2
	v_mov_b32_e32 v3, 0
	v_lshlrev_b32_e32 v2, 4, v4
	s_waitcnt lgkmcnt(0)
	v_lshl_add_u64 v[36:37], s[4:5], 0, v[2:3]
	v_lshl_add_u64 v[38:39], s[6:7], 0, v[2:3]
	v_lshlrev_b32_e32 v2, 3, v4
	v_lshl_add_u64 v[40:41], s[94:95], 0, v[2:3]
	v_mbcnt_hi_u32_b32 v2, -1, v199
	v_and_b32_e32 v3, 64, v2
	v_add_u32_e32 v3, 64, v3
	v_xor_b32_e32 v4, 1, v2
	v_cmp_lt_i32_e32 vcc, v4, v3
	v_mov_b32_e32 v55, 0x358637bd
	s_mov_b32 s13, 0xf800000
	v_cndmask_b32_e32 v4, v2, v4, vcc
	v_lshlrev_b32_e32 v35, 2, v4
	v_xor_b32_e32 v4, 2, v2
	v_cmp_lt_i32_e32 vcc, v4, v3
	v_mov_b32_e32 v56, 0x260
	s_mov_b32 s6, s78
	v_cndmask_b32_e32 v4, v2, v4, vcc
	v_lshlrev_b32_e32 v50, 2, v4
	v_xor_b32_e32 v4, 4, v2
	v_cmp_lt_i32_e32 vcc, v4, v3
	s_nop 1
	v_cndmask_b32_e32 v4, v2, v4, vcc
	v_lshlrev_b32_e32 v51, 2, v4
	v_xor_b32_e32 v4, 8, v2
	v_cmp_lt_i32_e32 vcc, v4, v3
	s_nop 1
	v_cndmask_b32_e32 v4, v2, v4, vcc
	v_lshlrev_b32_e32 v52, 2, v4
	v_xor_b32_e32 v4, 16, v2
	v_cmp_lt_i32_e32 vcc, v4, v3
	s_nop 1
	v_cndmask_b32_e32 v4, v2, v4, vcc
	v_lshlrev_b32_e32 v53, 2, v4
	v_xor_b32_e32 v4, 32, v2
	v_cmp_lt_i32_e32 vcc, v4, v3
	s_nop 1
	v_cndmask_b32_e32 v2, v2, v4, vcc
	v_lshlrev_b32_e32 v54, 2, v2
	global_load_dwordx4 v[208:211], v[38:39], off
	global_load_dwordx4 v[212:215], v[38:39], off offset:1024
	global_load_dwordx4 v[216:219], v[38:39], off offset:2048
	global_load_dwordx4 v[220:223], v[38:39], off offset:3072
	s_mov_b32 s98, s6
	s_mov_b32 s99, 0
	s_add_i32 s100, s6, s77
	s_cmp_lt_i32 s100, 0x10000
	s_cselect_b32 s100, s100, s6
	s_mov_b32 s101, 0
	s_lshl_b64 s[98:99], s[98:99], 12
	v_lshl_add_u64 v[204:205], v[36:37], 0, s[98:99]
	global_load_dwordx4 v[224:227], v[204:205], off
	global_load_dwordx4 v[228:231], v[204:205], off offset:1024
	global_load_dwordx4 v[232:235], v[204:205], off offset:3072
	global_load_dwordx4 v[236:239], v[204:205], off offset:2048
	s_lshl_b64 s[100:101], s[100:101], 12
	v_lshl_add_u64 v[206:207], v[36:37], 0, s[100:101]
	global_load_dwordx4 v[240:243], v[206:207], off
	global_load_dwordx4 v[244:247], v[206:207], off offset:1024
	global_load_dwordx4 v[248:251], v[206:207], off offset:3072
	global_load_dwordx4 v[200:203], v[206:207], off offset:2048
	s_waitcnt vmcnt(0)
	s_branch .LBB0_1323

; __device__ __forceinline__ void rms_pass(const float* X, const float* g, bf16_t* O, float* F, int rows, int gw, int NGW) {
;     ...
;     for (int m = gw; m < rows; m += 2 * NGW) {
;         const bool two = (m + NGW) < rows; const int m1 = two ? m + NGW : m;
;         const f32x4* x0 = (const f32x4*)(X + (size_t)m * 1024) + lane; const f32x4* x1 = (const f32x4*)(X + (size_t)m1 * 1024) + lane;
;         f32x4 v0[4], v1[4]; float s0 = 0.f, s1 = 0.f;
; #pragma unroll
;         for (int j = 0; j < 4; ++j) { v0[j] = x0[64 * j]; v1[j] = x1[64 * j]; }
; #pragma unroll
;         for (int j = 0; j < 4; ++j) { s0 += (v0[j].x * v0[j].x + v0[j].y * v0[j].y) + (v0[j].z * v0[j].z + v0[j].w * v0[j].w); s1 += (v1[j].x * v1[j].x + v1[j].y * v1[j].y) + (v1[j].z * v1[j].z + v1[j].w * v1[j].w); }
.LBB0_1323:
	s_add_i32 s26, s6, s77
	s_cmp_lt_i32 s26, 0x10000
	s_cselect_b64 s[14:15], -1, 0
	s_and_b64 s[8:9], s[14:15], exec
	s_cselect_b32 s8, s26, s6
	s_ashr_i32 s7, s6, 31
	s_lshl_b64 s[30:31], s[6:7], 12
	s_ashr_i32 s9, s8, 31
	s_waitcnt vmcnt(4)
	v_mov_b64_e32 v[26:27], v[224:225]
	v_mov_b64_e32 v[28:29], v[226:227]
	v_mov_b64_e32 v[18:19], v[228:229]
	v_mov_b64_e32 v[20:21], v[230:231]
	v_mov_b64_e32 v[2:3], v[232:233]
	v_mov_b64_e32 v[4:5], v[234:235]
	v_mov_b64_e32 v[14:15], v[236:237]
	v_mov_b64_e32 v[16:17], v[238:239]
	v_mov_b64_e32 v[30:31], v[240:241]
	v_mov_b64_e32 v[32:33], v[242:243]
	v_mov_b64_e32 v[22:23], v[244:245]
	v_mov_b64_e32 v[24:25], v[246:247]
	v_mov_b64_e32 v[6:7], v[248:249]
	v_mov_b64_e32 v[8:9], v[250:251]
	v_mov_b64_e32 v[10:11], v[200:201]
	v_mov_b64_e32 v[12:13], v[202:203]
	s_add_i32 s98, s26, s77
	s_cmp_lt_i32 s98, 0x10000
	s_cselect_b32 s98, s98, s6
	s_mov_b32 s99, 0
	s_add_i32 s100, s98, s77
	s_cmp_lt_i32 s100, 0x10000
	s_cselect_b32 s100, s100, s98
	s_mov_b32 s101, 0
	s_lshl_b64 s[98:99], s[98:99], 12
	v_lshl_add_u64 v[204:205], v[36:37], 0, s[98:99]
	global_load_dwordx4 v[224:227], v[204:205], off
	global_load_dwordx4 v[228:231], v[204:205], off offset:1024
	global_load_dwordx4 v[232:235], v[204:205], off offset:3072
	global_load_dwordx4 v[236:239], v[204:205], off offset:2048
	s_lshl_b64 s[100:101], s[100:101], 12
	v_lshl_add_u64 v[206:207], v[36:37], 0, s[100:101]
	global_load_dwordx4 v[240:243], v[206:207], off
	global_load_dwordx4 v[244:247], v[206:207], off offset:1024
	global_load_dwordx4 v[248:251], v[206:207], off offset:3072
	global_load_dwordx4 v[200:203], v[206:207], off offset:2048
	s_lshl_b64 s[30:31], s[6:7], 11
	s_lshl_b64 s[34:35], s[8:9], 11
	s_cmp_gt_i32 s26, 0xffff
	v_pk_mul_f32 v[42:43], v[28:29], v[28:29]
	v_pk_mul_f32 v[44:45], v[26:27], v[26:27]
	v_pk_mul_f32 v[46:47], v[20:21], v[20:21]
	v_pk_mul_f32 v[48:49], v[18:19], v[18:19]
	v_mul_f32_e32 v58, v15, v15
	v_mul_f32_e32 v60, v17, v17
	v_pk_mov_b32 v[62:63], v[44:45], v[42:43] op_sel:[1,0]
	v_mov_b32_e32 v45, v43
	v_pk_mul_f32 v[42:43], v[32:33], v[32:33]
	v_pk_mul_f32 v[64:65], v[30:31], v[30:31]
	v_pk_mov_b32 v[66:67], v[48:49], v[46:47] op_sel:[1,0]
	v_mov_b32_e32 v49, v47
	v_pk_mul_f32 v[46:47], v[24:25], v[24:25]
	v_pk_mul_f32 v[68:69], v[22:23], v[22:23]
	v_mul_f32_e32 v57, v4, v4
	v_mul_f32_e32 v71, v5, v5
	v_pk_fma_f32 v[58:59], v[14:15], v[14:15], v[58:59] op_sel_hi:[1,1,0]
	v_pk_fma_f32 v[60:61], v[16:17], v[16:17], v[60:61] op_sel_hi:[1,1,0]
	v_pk_add_f32 v[44:45], v[62:63], v[44:45]
	v_pk_mov_b32 v[62:63], v[64:65], v[42:43] op_sel:[1,0]
	v_mov_b32_e32 v65, v43
	v_pk_add_f32 v[42:43], v[66:67], v[48:49]
	v_pk_mov_b32 v[48:49], v[68:69], v[46:47] op_sel:[1,0]
	v_mov_b32_e32 v69, v47
	v_mul_f32_e32 v73, v2, v2
	v_mul_f32_e32 v74, v3, v3
	v_mov_b32_e32 v59, v57
	v_mov_b32_e32 v61, v71
	v_pk_add_f32 v[62:63], v[62:63], v[64:65]
	v_pk_add_f32 v[48:49], v[48:49], v[68:69]
	v_pk_add_f32 v[44:45], v[44:45], v[44:45] op_sel:[0,1] op_sel_hi:[1,0]
	v_pk_add_f32 v[42:43], v[42:43], v[42:43] op_sel:[0,1] op_sel_hi:[1,0]
	v_mul_f32_e32 v77, v6, v6
	v_mul_f32_e32 v78, v7, v7
	v_pk_add_f32 v[58:59], v[58:59], v[60:61]
	v_mov_b32_e32 v45, v73
	v_mov_b32_e32 v43, v74
	v_pk_add_f32 v[60:61], v[62:63], v[62:63] op_sel:[0,1] op_sel_hi:[1,0]
	v_pk_add_f32 v[48:49], v[48:49], v[48:49] op_sel:[0,1] op_sel_hi:[1,0]
	v_pk_add_f32 v[42:43], v[44:45], v[42:43]
	v_mov_b32_e32 v61, v77
	v_mov_b32_e32 v49, v78
	v_pk_add_f32 v[42:43], v[42:43], v[58:59]
	v_pk_add_f32 v[44:45], v[60:61], v[48:49]
	v_mul_f32_e32 v70, v11, v11
	v_mul_f32_e32 v72, v13, v13
	v_mul_f32_e32 v75, v8, v8
	v_mul_f32_e32 v76, v9, v9
	v_pk_fma_f32 v[46:47], v[10:11], v[10:11], v[70:71] op_sel_hi:[1,1,0]
	v_pk_fma_f32 v[66:67], v[12:13], v[12:13], v[72:73] op_sel_hi:[1,1,0]
	v_mov_b32_e32 v47, v75
	v_mov_b32_e32 v67, v76
	v_pk_add_f32 v[46:47], v[46:47], v[66:67]
	v_add_f32_e32 v48, v42, v43
	v_pk_add_f32 v[42:43], v[44:45], v[46:47]
	ds_bpermute_b32 v44, v35, v48
	v_add_f32_e32 v42, v42, v43
	ds_bpermute_b32 v43, v35, v42
	s_waitcnt lgkmcnt(1)
; __device__ __forceinline__ unsigned cvt_pk_bf16(float lo, float hi) { unsigned r; asm volatile("v_cvt_pk_bf16_f32 %0, %1, %2" : "=v"(r) : "v"(lo), "v"(hi)); return r; }
; __device__ __forceinline__ void rms_pass(const float* X, const float* g, bf16_t* O, float* F, int rows, int gw, int NGW) {
;     ...
;         for (int j = 0; j < 4; ++j) { s0 += (v0[j].x * v0[j].x + v0[j].y * v0[j].y) + (v0[j].z * v0[j].z + v0[j].w * v0[j].w); s1 += (v1[j].x * v1[j].x + v1[j].y * v1[j].y) + (v1[j].z * v1[j].z + v1[j].w * v1[j].w); }
;         const float r0 = 1.0f / sqrtf(wave_sum(s0) * (1.f / 1024.f) + 1e-6f), r1 = 1.0f / sqrtf(wave_sum(s1) * (1.f / 1024.f) + 1e-6f);
; #pragma unroll
;         for (int j = 0; j < 4; ++j) {
;             const f32x4 gg = gr[64 * j]; const f32x4 y0 = v0[j] * r0 * gg, y1 = v1[j] * r1 * gg;
;             u32x2 w0, w1; w0.x = cvt_pk_bf16(y0.x, y0.y); w0.y = cvt_pk_bf16(y0.z, y0.w); w1.x = cvt_pk_bf16(y1.x, y1.y); w1.y = cvt_pk_bf16(y1.z, y1.w);
;             *((u32x2*)(O + (size_t)m * 1024) + lane + 64 * j) = w0;
;             if (two) *((u32x2*)(O + (size_t)m1 * 1024) + lane + 64 * j) = w1;
	v_add_f32_e32 v44, v48, v44
	ds_bpermute_b32 v45, v50, v44
	s_waitcnt lgkmcnt(1)
	v_add_f32_e32 v42, v42, v43
	ds_bpermute_b32 v43, v50, v42
	s_waitcnt lgkmcnt(1)
	v_add_f32_e32 v44, v44, v45
	ds_bpermute_b32 v45, v51, v44
	s_waitcnt lgkmcnt(1)
	v_add_f32_e32 v42, v42, v43
	ds_bpermute_b32 v43, v51, v42
	s_waitcnt lgkmcnt(1)
	v_add_f32_e32 v44, v44, v45
	ds_bpermute_b32 v45, v52, v44
	s_waitcnt lgkmcnt(1)
	v_add_f32_e32 v42, v42, v43
	ds_bpermute_b32 v43, v52, v42
	s_waitcnt lgkmcnt(1)
	v_add_f32_e32 v44, v44, v45
	ds_bpermute_b32 v45, v53, v44
	s_waitcnt lgkmcnt(1)
	v_add_f32_e32 v42, v42, v43
	ds_bpermute_b32 v43, v53, v42
	s_waitcnt lgkmcnt(1)
	v_add_f32_e32 v44, v44, v45
	ds_bpermute_b32 v45, v54, v44
	s_waitcnt lgkmcnt(1)
	v_add_f32_e32 v42, v42, v43
	ds_bpermute_b32 v43, v54, v42
	s_waitcnt lgkmcnt(1)
	v_add_f32_e32 v44, v44, v45
	v_fmamk_f32 v44, v44, 0x3a800000, v55
	s_waitcnt lgkmcnt(0)
	v_add_f32_e32 v42, v42, v43
	v_mul_f32_e32 v43, 0x4f800000, v44
	v_cmp_gt_f32_e32 vcc, s13, v44
	v_fmamk_f32 v42, v42, 0x3a800000, v55
	v_cmp_gt_f32_e64 s[6:7], s13, v42
	v_cndmask_b32_e32 v43, v44, v43, vcc
	v_mul_f32_e32 v44, 0x4f800000, v42
	v_sqrt_f32_e32 v45, v43
	v_cndmask_b32_e64 v42, v42, v44, s[6:7]
	v_sqrt_f32_e32 v44, v42
	v_add_u32_e32 v46, -1, v45
	v_add_u32_e32 v47, 1, v45
	v_fma_f32 v48, -v46, v45, v43
	v_fma_f32 v49, -v47, v45, v43
	v_add_u32_e32 v57, -1, v44
	v_cmp_ge_f32_e64 s[8:9], 0, v48
	v_add_u32_e32 v62, 1, v44
	v_fma_f32 v48, -v62, v44, v42
	v_cndmask_b32_e64 v45, v45, v46, s[8:9]
	v_fma_f32 v46, -v57, v44, v42
	v_cmp_lt_f32_e64 s[8:9], 0, v49
	s_nop 1
	v_cndmask_b32_e64 v45, v45, v47, s[8:9]
	v_cmp_ge_f32_e64 s[8:9], 0, v46
	v_mul_f32_e32 v46, 0x37800000, v45
	v_cndmask_b32_e32 v45, v45, v46, vcc
	v_cndmask_b32_e64 v44, v44, v57, s[8:9]
	v_cmp_lt_f32_e64 s[8:9], 0, v48
	v_cmp_class_f32_e32 vcc, v43, v56
	s_nop 0
	v_cndmask_b32_e64 v44, v44, v62, s[8:9]
	v_mul_f32_e32 v46, 0x37800000, v44
	v_cndmask_b32_e32 v43, v45, v43, vcc
	v_cndmask_b32_e64 v44, v44, v46, s[6:7]
	v_div_scale_f32 v45, s[6:7], v43, v43, 1.0
	v_cmp_class_f32_e64 s[6:7], v42, v56
	v_div_scale_f32 v46, vcc, 1.0, v43, 1.0
	s_nop 0
	v_cndmask_b32_e64 v42, v44, v42, s[6:7]
	v_rcp_f32_e32 v44, v45
	v_div_scale_f32 v47, s[6:7], v42, v42, 1.0
	v_rcp_f32_e32 v49, v47
	v_fma_f32 v48, -v45, v44, 1.0
	v_fmac_f32_e32 v44, v48, v44
	v_mul_f32_e32 v62, v46, v44
	v_fma_f32 v48, -v47, v49, 1.0
	v_fmac_f32_e32 v49, v48, v49
	v_fma_f32 v48, -v45, v62, v46
	v_fmac_f32_e32 v62, v48, v44
	v_fma_f32 v45, -v45, v62, v46
	v_div_scale_f32 v57, s[6:7], 1.0, v42, 1.0
	v_div_fmas_f32 v44, v45, v44, v62
	v_div_fixup_f32 v48, v44, v43, 1.0
	v_mul_f32_e32 v43, v57, v49
	v_fma_f32 v44, -v47, v43, v57
	v_fmac_f32_e32 v43, v44, v49
	v_fma_f32 v44, -v47, v43, v57
	s_mov_b64 vcc, s[6:7]
	v_div_fmas_f32 v43, v44, v49, v43
	v_div_fixup_f32 v46, v43, v42, 1.0
	v_pk_mul_f32 v[26:27], v[26:27], v[48:49] op_sel_hi:[1,0]
	v_lshl_add_u64 v[44:45], v[40:41], 0, s[30:31]
	v_lshl_add_u64 v[42:43], v[40:41], 0, s[34:35]
	v_pk_mul_f32 v[28:29], v[28:29], v[48:49] op_sel_hi:[1,0]
	v_pk_mul_f32 v[26:27], v[208:209], v[26:27]
	v_pk_mul_f32 v[30:31], v[30:31], v[46:47] op_sel_hi:[1,0]
	v_pk_mul_f32 v[32:33], v[32:33], v[46:47] op_sel_hi:[1,0]
	v_pk_mul_f32 v[28:29], v[210:211], v[28:29]
	v_pk_mul_f32 v[32:33], v[210:211], v[32:33]
	v_pk_mul_f32 v[30:31], v[208:209], v[30:31]
	v_cvt_pk_bf16_f32 v58, v26, v27
	v_cvt_pk_bf16_f32 v59, v28, v29
	s_nop 0
	v_cvt_pk_bf16_f32 v26, v30, v31
	v_cvt_pk_bf16_f32 v27, v32, v33
	global_store_dwordx2 v[44:45], v[58:59], off
	s_cbranch_scc1 .LBB0_1325
	global_store_dwordx2 v[42:43], v[26:27], off

; __global__ void __launch_bounds__(512, 2) fwd_megakernel(Params p) {
	.amdhsa_kernel _Z14fwd_megakernel6Params
		.amdhsa_group_segment_fixed_size 0
		.amdhsa_private_segment_fixed_size 0
		.amdhsa_kernarg_size 504
		.amdhsa_user_sgpr_count 2
		.amdhsa_user_sgpr_dispatch_ptr 0
		.amdhsa_user_sgpr_queue_ptr 0
		.amdhsa_user_sgpr_kernarg_segment_ptr 1
		.amdhsa_user_sgpr_dispatch_id 0
		.amdhsa_user_sgpr_kernarg_preload_length 0
		.amdhsa_user_sgpr_kernarg_preload_offset 0
		.amdhsa_user_sgpr_private_segment_size 0
		.amdhsa_uses_dynamic_stack 0
		.amdhsa_enable_private_segment 0
		.amdhsa_system_sgpr_workgroup_id_x 1
		.amdhsa_system_sgpr_workgroup_id_y 0
		.amdhsa_system_sgpr_workgroup_id_z 0
		.amdhsa_system_sgpr_workgroup_info 0
		.amdhsa_system_vgpr_workitem_id 2
		.amdhsa_next_free_vgpr 256
		.amdhsa_next_free_sgpr 102
		.amdhsa_accum_offset 256
		.amdhsa_reserve_vcc 1
		.amdhsa_float_round_mode_32 0
		.amdhsa_float_round_mode_16_64 0
		.amdhsa_float_denorm_mode_32 3
		.amdhsa_float_denorm_mode_16_64 3
		.amdhsa_dx10_clamp 1
		.amdhsa_ieee_mode 1
		.amdhsa_fp16_overflow 0
		.amdhsa_tg_split 0
		.amdhsa_exception_fp_ieee_invalid_op 0
		.amdhsa_exception_fp_denorm_src 0
		.amdhsa_exception_fp_ieee_div_zero 0
		.amdhsa_exception_fp_ieee_overflow 0
		.amdhsa_exception_fp_ieee_underflow 0
		.amdhsa_exception_fp_ieee_inexact 0
		.amdhsa_exception_int_div_zero 0
	.end_amdhsa_kernel

; __global__ void __launch_bounds__(512, 2) fwd_megakernel(Params p) {
amdhsa.kernels:
  - .agpr_count:     0
    .args:
      - .offset:         0
        .size:           248
        .value_kind:     by_value
      - .offset:         248
        .size:           4
        .value_kind:     hidden_block_count_x
      - .offset:         252
        .size:           4
        .value_kind:     hidden_block_count_y
      - .offset:         256
        .size:           4
        .value_kind:     hidden_block_count_z
      - .offset:         260
        .size:           2
        .value_kind:     hidden_group_size_x
      - .offset:         262
        .size:           2
        .value_kind:     hidden_group_size_y
      - .offset:         264
        .size:           2
        .value_kind:     hidden_group_size_z
      - .offset:         266
        .size:           2
        .value_kind:     hidden_remainder_x
      - .offset:         268
        .size:           2
        .value_kind:     hidden_remainder_y
      - .offset:         270
        .size:           2
        .value_kind:     hidden_remainder_z
      - .offset:         288
        .size:           8
        .value_kind:     hidden_global_offset_x
      - .offset:         296
        .size:           8
        .value_kind:     hidden_global_offset_y
      - .offset:         304
        .size:           8
        .value_kind:     hidden_global_offset_z
      - .offset:         312
        .size:           2
        .value_kind:     hidden_grid_dims
      - .offset:         336
        .size:           8
        .value_kind:     hidden_multigrid_sync_arg
      - .offset:         368
        .size:           4
        .value_kind:     hidden_dynamic_lds_size
    .group_segment_fixed_size: 0
    .kernarg_segment_align: 8
    .kernarg_segment_size: 504
    .language:       OpenCL C
    .language_version:
      - 2
      - 0
    .max_flat_workgroup_size: 512
    .name:           _Z14fwd_megakernel6Params
    .private_segment_fixed_size: 0
    .sgpr_count:     108
    .sgpr_spill_count: 72
    .symbol:         _Z14fwd_megakernel6Params.kd
    .uniform_work_group_size: 1
    .uses_dynamic_stack: false
    .vgpr_count:     256
    .vgpr_spill_count: 0
    .wavefront_size: 64
